# MLP weight conversion moved from the head of the out-projection phase into the start of the second half's attention phase (waves 0-3 convert while waves 4-7 run attention units)
# speedup vs baseline: 1.0003x; 1.0003x over previous
.LBB0_346:
	s_or_b64 exec, exec, s[4:5]
	s_xor_b64 s[46:47], s[0:1], -1
	s_lshl_b32 s0, s48, 9
	v_readlane_b32 s1, v254, 57
	s_or_b32 s76, s0, s1
	v_mov_b32_e32 v0, v236
	s_mov_b64 s[0:1], s[38:39]
	s_waitcnt lgkmcnt(0)
	s_barrier
	s_load_dwordx2 s[4:5], s[0:1], 0x80
	v_readfirstlane_b32 s3, v0
	s_lshl_b32 s3, s3, 8
	s_and_b32 s3, s3, 0xffffc000
	s_add_i32 s49, s3, 0
	s_lshl_b64 s[6:7], s[76:77], 2
	s_waitcnt lgkmcnt(0)
	s_add_u32 s3, s4, s6
	s_addc_u32 s4, s5, s7
	v_readlane_b32 s5, v254, 27
	v_and_b32_e32 v246, 63, v0
	s_add_u32 s40, s3, s5
	s_addc_u32 s41, s4, 0
	v_cmp_eq_u32_e64 s[18:19], 0, v246
	s_cmp_lg_u32 s48, 1
	s_cbranch_scc1 .Lc2_skip
	v_readfirstlane_b32 s99, v236
	s_cmpk_ge_u32 s99, 0x100
	s_cbranch_scc1 .Lc2_skip
	v_mov_b32_e32 v80, v2
	v_mov_b32_e32 v81, v3
	v_mov_b32_e32 v82, v4
	v_mov_b32_e32 v83, v5
	v_mov_b32_e32 v84, v6
	v_mov_b32_e32 v85, v7
	v_mov_b32_e32 v86, v8
	v_mov_b32_e32 v87, v9
	v_mov_b32_e32 v88, v10
	v_mov_b32_e32 v89, v11
	v_mov_b32_e32 v90, v12
	v_mov_b32_e32 v91, v13
	v_mov_b32_e32 v92, v14
	v_mov_b32_e32 v93, v15
	v_mov_b32_e32 v94, v16
	v_mov_b32_e32 v95, v17
	v_mov_b32_e32 v96, v18
	v_mov_b32_e32 v97, v19
	v_mov_b32_e32 v138, v20
	v_mov_b32_e32 v139, v21
	v_mov_b32_e32 v160, v22
	v_mov_b32_e32 v162, v23
	v_mov_b32_e32 v164, v24
	v_mov_b32_e32 v166, v25
	v_mov_b32_e32 v182, v26
	v_mov_b32_e32 v183, v27
	v_mov_b32_e32 v184, v28
	v_mov_b32_e32 v185, v29
	v_mov_b32_e32 v188, v30
	v_mov_b32_e32 v189, v31
	v_mov_b32_e32 v190, v32
	v_mov_b32_e32 v192, v33
	v_mov_b32_e32 v194, v34
	v_mov_b32_e32 v195, v35
	v_mov_b32_e32 v196, v38
	v_mov_b32_e32 v197, v39
	v_mov_b32_e32 v198, v50
	v_mov_b32_e32 v199, v51
	v_mov_b32_e32 v200, v142
	v_mov_b32_e32 v202, v143
	v_mov_b32_e32 v203, v144
	v_mov_b32_e32 v204, v145
	v_mov_b32_e32 v205, v146
	v_mov_b32_e32 v206, v147
	v_mov_b32_e32 v207, v148
	v_mov_b32_e32 v208, v149
	v_mov_b32_e32 v209, v150
	v_mov_b32_e32 v210, v151
	v_mov_b32_e32 v211, v152
	v_mov_b32_e32 v214, v153
	v_mov_b32_e32 v215, v154
	v_mov_b32_e32 v216, v155
	v_mov_b32_e32 v217, v156
	v_mov_b32_e32 v218, v157
	v_mov_b32_e32 v219, v158
	v_mov_b32_e32 v220, v159
	v_mov_b32_e32 v221, v168
	v_mov_b32_e32 v224, v169
	v_mov_b32_e32 v225, v170
	v_mov_b32_e32 v226, v171
	v_mov_b32_e32 v227, v172
	v_mov_b32_e32 v228, v173
	v_mov_b32_e32 v230, v174
	v_mov_b32_e32 v231, v175
	v_mov_b32_e32 v232, v176
	v_mov_b32_e32 v233, v177
	v_mov_b32_e32 v234, v178
	v_mov_b32_e32 v235, v179
	v_mov_b32_e32 v239, v180
	v_mov_b32_e32 v247, v181
	v_writelane_b32 v253, s0, 0
	v_writelane_b32 v253, s1, 1
	v_writelane_b32 v253, s3, 2
	v_writelane_b32 v253, s15, 3
	v_writelane_b32 v253, s18, 4
	v_writelane_b32 v253, s19, 5
	s_lshr_b32 s99, s83, 1
	s_movk_i32 s100, 0x400
	s_movk_i32 s101, 0xfff
	s_branch .Lc2_entry
.Lc2_return:
	v_mov_b32_e32 v2, v80
	v_mov_b32_e32 v3, v81
	v_mov_b32_e32 v4, v82
	v_mov_b32_e32 v5, v83
	v_mov_b32_e32 v6, v84
	v_mov_b32_e32 v7, v85
	v_mov_b32_e32 v8, v86
	v_mov_b32_e32 v9, v87
	v_mov_b32_e32 v10, v88
	v_mov_b32_e32 v11, v89
	v_mov_b32_e32 v12, v90
	v_mov_b32_e32 v13, v91
	v_mov_b32_e32 v14, v92
	v_mov_b32_e32 v15, v93
	v_mov_b32_e32 v16, v94
	v_mov_b32_e32 v17, v95
	v_mov_b32_e32 v18, v96
	v_mov_b32_e32 v19, v97
	v_mov_b32_e32 v20, v138
	v_mov_b32_e32 v21, v139
	v_mov_b32_e32 v22, v160
	v_mov_b32_e32 v23, v162
	v_mov_b32_e32 v24, v164
	v_mov_b32_e32 v25, v166
	v_mov_b32_e32 v26, v182
	v_mov_b32_e32 v27, v183
	v_mov_b32_e32 v28, v184
	v_mov_b32_e32 v29, v185
	v_mov_b32_e32 v30, v188
	v_mov_b32_e32 v31, v189
	v_mov_b32_e32 v32, v190
	v_mov_b32_e32 v33, v192
	v_mov_b32_e32 v34, v194
	v_mov_b32_e32 v35, v195
	v_mov_b32_e32 v38, v196
	v_mov_b32_e32 v39, v197
	v_mov_b32_e32 v50, v198
	v_mov_b32_e32 v51, v199
	v_mov_b32_e32 v142, v200
	v_mov_b32_e32 v143, v202
	v_mov_b32_e32 v144, v203
	v_mov_b32_e32 v145, v204
	v_mov_b32_e32 v146, v205
	v_mov_b32_e32 v147, v206
	v_mov_b32_e32 v148, v207
	v_mov_b32_e32 v149, v208
	v_mov_b32_e32 v150, v209
	v_mov_b32_e32 v151, v210
	v_mov_b32_e32 v152, v211
	v_mov_b32_e32 v153, v214
	v_mov_b32_e32 v154, v215
	v_mov_b32_e32 v155, v216
	v_mov_b32_e32 v156, v217
	v_mov_b32_e32 v157, v218
	v_mov_b32_e32 v158, v219
	v_mov_b32_e32 v159, v220
	v_mov_b32_e32 v168, v221
	v_mov_b32_e32 v169, v224
	v_mov_b32_e32 v170, v225
	v_mov_b32_e32 v171, v226
	v_mov_b32_e32 v172, v227
	v_mov_b32_e32 v173, v228
	v_mov_b32_e32 v174, v230
	v_mov_b32_e32 v175, v231
	v_mov_b32_e32 v176, v232
	v_mov_b32_e32 v177, v233
	v_mov_b32_e32 v178, v234
	v_mov_b32_e32 v179, v235
	v_mov_b32_e32 v180, v239
	v_mov_b32_e32 v181, v247
	v_readlane_b32 s0, v253, 0
	v_readlane_b32 s1, v253, 1
	v_readlane_b32 s3, v253, 2
	v_readlane_b32 s15, v253, 3
	v_readlane_b32 s18, v253, 4
	v_readlane_b32 s19, v253, 5
	s_nop 4
.Lc2_skip:
	s_branch .LBB0_350
.LBB0_347:
	s_or_b64 exec, exec, s[4:5]

.LBB0_703:
	s_or_b64 exec, exec, s[4:5]
	s_mov_b64 s[4:5], exec
	v_mbcnt_lo_u32_b32 v0, s4, 0
	v_mbcnt_hi_u32_b32 v0, s5, v0
	v_cmp_eq_u32_e32 vcc, 0, v0
	s_waitcnt vmcnt(0)
	buffer_inv sc1
	s_and_saveexec_b64 s[8:9], vcc
	s_cbranch_execz .LBB0_165
	s_bcnt1_i32_b64 s3, s[4:5]
	v_mov_b32_e32 v0, s3
	global_atomic_add v238, v0, s[6:7] offset:1024
	s_branch .LBB0_165
.LBB0_705:
	s_branch .LBB0_776
.Lc2_entry:
	v_mov_b32_e32 v0, v236
	s_nop 0
	v_readfirstlane_b32 s0, v0
	s_ashr_i32 s4, s0, 6
	s_add_i32 s3, s4, s99
	s_mov_b64 s[0:1], s[38:39]
	s_cmp_le_i32 s3, s101
	s_cbranch_scc0 .Lc2_return
	s_load_dwordx4 s[12:15], s[0:1], 0x60
	s_load_dwordx2 s[6:7], s[0:1], 0x58
	v_readlane_b32 s18, v254, 60
	v_readlane_b32 s19, v254, 61
	s_lshl_b64 s[8:9], s[18:19], 24
	s_load_dwordx2 s[16:17], s[0:1], 0x80
	s_waitcnt lgkmcnt(0)
	s_add_u32 s0, s12, s8
	s_addc_u32 s1, s13, s9
	s_add_u32 s8, s14, s8
	s_addc_u32 s9, s15, s9
	s_lshl_b64 s[12:13], s[18:19], 12
	v_and_b32_e32 v10, 31, v0
	v_bfe_u32 v11, v0, 5, 1
	v_bfe_u32 v14, v0, 3, 3
	v_lshlrev_b32_e32 v0, 3, v0
	s_add_u32 s12, s6, s12
	v_and_b32_e32 v0, 56, v0
	s_addc_u32 s13, s7, s13
	s_lshl_b32 s4, s4, 14
	v_mul_u32_u24_e32 v4, 0x84, v0
	v_lshlrev_b32_e32 v0, 1, v0
	s_add_i32 s14, s4, 0
	v_lshl_add_u64 v[6:7], s[16:17], 0, v[0:1]
	s_mov_b64 s[4:5], 0xa00000
	v_lshlrev_b32_e32 v0, 2, v14
	v_lshl_add_u64 v[2:3], v[6:7], 0, s[4:5]
	v_add3_u32 v15, s14, v4, v0
	v_lshlrev_b32_e32 v0, 2, v11
	s_cmp_lg_u64 s[6:7], 0
	s_mov_b64 s[4:5], 0x200000
	v_lshl_add_u64 v[4:5], s[12:13], 0, v[0:1]
	s_cselect_b64 s[12:13], -1, 0
	v_lshl_add_u64 v[6:7], v[6:7], 0, s[4:5]
	s_lshl_b32 s4, s3, 1
	v_lshl_add_u32 v12, v10, 2, s14
	v_mul_u32_u24_e32 v13, 0x84, v11
	v_or_b32_e32 v16, 8, v14
	v_or_b32_e32 v17, 16, v14
	v_or_b32_e32 v18, 24, v14
	s_lshl_b32 s16, s3, 5
	s_lshl_b32 s17, s100, 5
	s_add_i32 s18, s4, 0x1f000
	s_lshl_b32 s19, s100, 1
	s_branch .LBB0_709

.LBB0_708:
	s_add_i32 s3, s3, s100
	s_add_i32 s16, s16, s17
	s_add_i32 s18, s18, s19
	s_cmp_gt_i32 s3, s101
	s_cbranch_scc1 .Lc2_return
